# speedup vs baseline: 1.0109x; 1.0079x over previous
; __device__ __forceinline__ unsigned xb_ld(unsigned* p)              { return __hip_atomic_load(p, __ATOMIC_RELAXED, __HIP_MEMORY_SCOPE_AGENT); }
; #define XB_SPIN(cond, bar) do { unsigned _sp = 0; while (cond) { __builtin_amdgcn_s_sleep(1); \
;     if ((++_sp & 255u) == 0u) { if (xb_ld(&(bar)[XB_TMO])) break; if (_sp > XB_SPIN_CAP) { atomicAdd(&(bar)[XB_TMO], 1u); break; } } } } while (0)
; __device__ __forceinline__ void xcd_barrier(const XcdBarrier& b) {
;     ...
;       XB_SPIN(xb_ld(&bar[XB_XGEN(b.x)]) == gen, bar);
;       __builtin_amdgcn_fence(__ATOMIC_ACQUIRE, "agent");
;       asm volatile("s_waitcnt vmcnt(0)" ::: "memory");
.LBB0_855:
	s_or_b64 exec, exec, s[40:41]
	s_waitcnt vmcnt(0)
	buffer_inv sc0
	s_waitcnt vmcnt(0)

; __device__ __forceinline__ unsigned xb_ld(unsigned* p)              { return __hip_atomic_load(p, __ATOMIC_RELAXED, __HIP_MEMORY_SCOPE_AGENT); }
; #define XB_SPIN(cond, bar) do { unsigned _sp = 0; while (cond) { __builtin_amdgcn_s_sleep(1); \
;     if ((++_sp & 255u) == 0u) { if (xb_ld(&(bar)[XB_TMO])) break; if (_sp > XB_SPIN_CAP) { atomicAdd(&(bar)[XB_TMO], 1u); break; } } } } while (0)
; __device__ __forceinline__ void xcd_barrier(const XcdBarrier& b) {
;     ...
;       XB_SPIN(xb_ld(&bar[XB_XGEN(b.x)]) == gen, bar);
;       __builtin_amdgcn_fence(__ATOMIC_ACQUIRE, "agent");
;       asm volatile("s_waitcnt vmcnt(0)" ::: "memory");
.LBB0_930:
	s_or_b64 exec, exec, s[38:39]
	s_waitcnt vmcnt(0)
	buffer_inv sc0
	s_waitcnt vmcnt(0)
